# slc phase: dynamic unit tickets from a device counter after the first static unit (load balance)
# baseline (speedup 1.0000x reference)
; __global__ void __launch_bounds__(256, 2) mega_kernel(Params p) {
;     ...
;   unsigned bk = 0;
;   if (blockIdx.x == 0 && threadIdx.x < 17) __hip_atomic_store(p.bar + 64 * threadIdx.x, 0u, __ATOMIC_RELAXED, __HIP_MEMORY_SCOPE_AGENT);
_Z11mega_kernel6Params:
	s_mov_b64 s[80:81], s[0:1]
	s_mov_b32 s86, s2
	s_add_u32 s2, s80, 0x9e0
	s_load_dword s82, s[0:1], 0x9e0
	s_addc_u32 s3, s81, 0
	s_cmp_eq_u32 s86, 0
	v_and_b32_e32 v167, 0x3ff, v0
	s_cselect_b64 s[0:1], -1, 0
	v_cmp_gt_u32_e32 vcc, 18, v167
	s_and_b64 s[0:1], s[0:1], vcc
	s_and_saveexec_b64 s[4:5], s[0:1]
	s_cbranch_execz .LBB0_2
	s_load_dwordx2 s[0:1], s[80:81], 0xe0
	v_lshlrev_b32_e32 v1, 8, v167
	v_mov_b32_e32 v2, 0
	s_waitcnt lgkmcnt(0)
	global_store_dword v1, v2, s[0:1] sc1

; __global__ void __launch_bounds__(256, 2) mega_kernel(Params p) {
;     ...
;       for (int u = blockIdx.x; u < 4096; u += G) {
;         const int v = balance_unit(u, G), ch = 255 - (v >> 4), gb = v & 15;
;         nsa_slc_unit(p, ((gb >> 1) << 9) | ((gb & 1) << 8) | ch, smem);
;       }
.LBB0_728:
	s_or_b64 exec, exec, s[2:3]
	s_load_dwordx2 s[100:101], s[80:81], 0xe0
	s_waitcnt lgkmcnt(0)
	s_add_u32 s100, s100, 0x1100
	s_addc_u32 s101, s101, 0
	v_mov_b32_e32 v252, s100
	v_mov_b32_e32 v253, s101
	v_mov_b32_e32 v254, 1
	v_mov_b32_e32 v255, 0x128e0
	v_readlane_b32 s2, v230, 8
	v_readlane_b32 s3, v230, 9
	s_andn2_b64 vcc, exec, s[2:3]
	s_mov_b32 s1, s86
	s_barrier
	s_cbranch_vccz .LBB0_813

; DI unsigned pack2(float a, float b) { f32x2 v = {a, b}; bf16x2_t r = __builtin_convertvector(v, bf16x2_t); return __builtin_bit_cast(unsigned, r); }
; DI float bflo(unsigned v) { return __uint_as_float(v << 16); }
; DI float bfhi(unsigned v) { return __uint_as_float(v & 0xffff0000u); }
; DI size_t blk(size_t row, int k, int R) { return ((size_t)(k >> 5) * R + row) * 32 + (k & 31); }
; DI float silu_f(float x) { return x / (1.f + __expf(-x)); }
; DI void nsa_slc_unit(const Params& p, int u, char* smem, bool probe = false) {
;     ...
;   l += __shfl_xor(l, 32);
;   const float inv = 1.f / l;
;   const float g0 = p.gates[tok * 48 + head * 3], g1 = p.gates[tok * 48 + head * 3 + 1] * inv, g2 = p.gates[tok * 48 + head * 3 + 2];
;   const bf16_t* oc = p.Q + (size_t)NTOK * 1024 + tok * 1024 + head * 64; const bf16_t* ow = p.Q + (size_t)2 * NTOK * 1024 + tok * 1024 + head * 64;
; #pragma unroll
;   for (int dt = 0; dt < 2; ++dt)
; #pragma unroll
;     for (int g4 = 0; g4 < 4; ++g4) {
;       const int d = 32 * dt + 8 * g4 + 4 * h;
;       bf16_t* gp = p.G + blk(tok, head * 64 + d, NTOK);
;       const u32x2 cv = *(const u32x2*)(oc + d), wv = *(const u32x2*)(ow + d), gv = *(const u32x2*)gp;
;       const float a0 = (g0 * bflo(cv[0]) + g1 * o[dt][4 * g4] + g2 * bflo(wv[0])) * silu_f(bflo(gv[0]));
;       const float a1 = (g0 * bfhi(cv[0]) + g1 * o[dt][4 * g4 + 1] + g2 * bfhi(wv[0])) * silu_f(bfhi(gv[0]));
;       const float a2 = (g0 * bflo(cv[1]) + g1 * o[dt][4 * g4 + 2] + g2 * bflo(wv[1])) * silu_f(bflo(gv[1]));
;       const float a3 = (g0 * bfhi(cv[1]) + g1 * o[dt][4 * g4 + 3] + g2 * bfhi(wv[1])) * silu_f(bfhi(gv[1]));
;       *(u32x2*)gp = (u32x2){pack2(a0, a1), pack2(a2, a3)};
.LBB0_812:
	v_and_b32_e32 v34, 64, v202
	v_xor_b32_e32 v0, 32, v202
	v_add_u32_e32 v34, 64, v34
	v_cmp_lt_i32_e32 vcc, v0, v34
	v_readlane_b32 s36, v230, 51
	v_readlane_b32 s44, v230, 59
	v_cndmask_b32_e32 v0, v202, v0, vcc
	v_lshlrev_b32_e32 v0, 2, v0
	ds_bpermute_b32 v0, v0, v213
	v_readlane_b32 s45, v230, 60
	s_movk_i32 s4, 0xc0
	v_lshlrev_b64 v[40:41], 1, v[182:183]
	v_mov_b32_e32 v185, v1
	s_waitcnt lgkmcnt(0)
	v_add_f32_e32 v0, v213, v0
	v_div_scale_f32 v34, s[2:3], v0, v0, 1.0
	v_rcp_f32_e32 v35, v34
	v_lshrrev_b32_e32 v37, 3, v210
	v_readlane_b32 s38, v230, 53
	v_readlane_b32 s39, v230, 54
	v_fma_f32 v36, -v34, v35, 1.0
	v_fmac_f32_e32 v35, v36, v35
	v_div_scale_f32 v36, vcc, 1.0, v0, 1.0
	v_mul_f32_e32 v38, v36, v35
	v_fma_f32 v39, -v34, v38, v36
	v_fmac_f32_e32 v38, v39, v35
	v_fma_f32 v34, -v34, v38, v36
	v_div_fmas_f32 v34, v34, v35, v38
	v_div_fixup_f32 v38, v34, v0, 1.0
	v_mov_b64_e32 v[34:35], s[44:45]
	v_mad_u64_u32 v[34:35], s[2:3], v180, s4, v[34:35]
	v_readlane_b32 s2, v229, 3
	v_readlane_b32 s3, v229, 4
	v_mul_u32_u24_e32 v0, 3, v209
	v_mad_i32_i24 v35, v181, s4, v35
	v_lshl_add_u64 v[42:43], s[2:3], 0, v[40:41]
	v_readlane_b32 s2, v230, 16
	v_lshlrev_b32_e32 v0, 2, v0
	v_readlane_b32 s3, v230, 17
	v_lshl_add_u64 v[34:35], v[34:35], 0, v[0:1]
	v_lshlrev_b32_e32 v0, 16, v209
	v_lshl_add_u64 v[40:41], s[2:3], 0, v[40:41]
	v_lshl_add_u64 v[48:49], v[40:41], 0, v[184:185]
	v_lshl_add_u64 v[40:41], v[180:181], 0, v[0:1]
	v_and_b32_e32 v37, 4, v37
	v_lshlrev_b64 v[40:41], 6, v[40:41]
	v_lshl_add_u64 v[42:43], v[42:43], 0, v[184:185]
	v_lshl_add_u64 v[40:41], s[38:39], 0, v[40:41]
	v_lshlrev_b32_e32 v44, 1, v37
	v_mov_b32_e32 v45, v1
	v_lshl_add_u64 v[46:47], v[40:41], 0, v[44:45]
	v_lshl_add_u64 v[40:41], v[42:43], 0, v[44:45]
	global_load_dwordx2 v[50:51], v[40:41], off
	v_lshl_add_u64 v[42:43], v[48:49], 0, v[44:45]
	global_load_dwordx3 v[34:36], v[34:35], off
	s_nop 0
	global_load_dwordx2 v[48:49], v[42:43], off
	global_load_dwordx2 v[52:53], v[46:47], off
	v_or_b32_e32 v0, 0x8000, v0
	v_cmp_eq_u32_e64 s[100:101], 0, v167
	s_and_saveexec_b64 s[100:101], s[100:101]
	s_cbranch_execz .Ltk_skip2
	s_waitcnt vmcnt(4)
	v_add_u32_e32 v250, s82, v250
	ds_write_b32 v255, v250
.Ltk_skip2:
	s_mov_b64 exec, s[100:101]
	s_waitcnt lgkmcnt(0)
	s_barrier
	ds_read_b32 v251, v255
	s_waitcnt lgkmcnt(0)
	v_readfirstlane_b32 s1, v251
	s_nop 3
	s_cmpk_lt_i32 s1, 0x1000
	v_readlane_b32 s37, v230, 52
	v_readlane_b32 s40, v230, 55
	v_readlane_b32 s41, v230, 56
	v_readlane_b32 s42, v230, 57
	v_readlane_b32 s43, v230, 58
	v_readlane_b32 s46, v230, 61
	v_readlane_b32 s47, v230, 62
	v_readlane_b32 s48, v230, 63
	v_readlane_b32 s49, v229, 0
	v_readlane_b32 s50, v229, 1
	v_readlane_b32 s51, v229, 2
	s_waitcnt vmcnt(3)
	v_lshlrev_b32_e32 v56, 16, v50
	v_and_b32_e32 v57, 0xffff0000, v50
	s_waitcnt vmcnt(2)
	v_mul_f32_e32 v38, v35, v38
	s_waitcnt vmcnt(0)
	v_lshlrev_b32_e32 v39, 16, v52
	v_pk_mul_f32 v[56:57], v[34:35], v[56:57] op_sel_hi:[0,1]
	v_and_b32_e32 v52, 0xffff0000, v52
	v_mul_f32_e32 v37, 0xbfb8aa3b, v39
	v_pk_fma_f32 v[56:57], v[2:3], v[38:39], v[56:57] op_sel_hi:[1,0,1]
	v_lshlrev_b32_e32 v58, 16, v48
	v_and_b32_e32 v59, 0xffff0000, v48
	v_mov_b32_e32 v2, v36
	v_exp_f32_e32 v54, v37
	v_pk_fma_f32 v[36:37], v[2:3], v[58:59], v[56:57] op_sel_hi:[0,1,1]
	v_mul_f32_e32 v3, 0xbfb8aa3b, v52
	v_exp_f32_e32 v55, v3
	s_nop 0
	v_pk_add_f32 v[54:55], v[54:55], 1.0 op_sel_hi:[1,0]
	s_nop 0
	v_div_scale_f32 v3, s[2:3], v55, v55, v52
	v_rcp_f32_e32 v48, v3
	s_nop 0
	v_fma_f32 v50, -v3, v48, 1.0
	v_fmac_f32_e32 v48, v50, v48
	v_div_scale_f32 v50, vcc, v52, v55, v52
	v_mul_f32_e32 v56, v50, v48
	v_fma_f32 v57, -v3, v56, v50
	v_fmac_f32_e32 v56, v57, v48
	v_fma_f32 v3, -v3, v56, v50
	v_div_fmas_f32 v3, v3, v48, v56
	v_div_fixup_f32 v55, v3, v55, v52
	v_div_scale_f32 v3, s[2:3], v54, v54, v39
	v_rcp_f32_e32 v48, v3
	s_nop 0
	v_fma_f32 v50, -v3, v48, 1.0
	v_fmac_f32_e32 v48, v50, v48
	v_div_scale_f32 v50, vcc, v39, v54, v39
	v_mul_f32_e32 v52, v50, v48
	v_fma_f32 v56, -v3, v52, v50
	v_fmac_f32_e32 v52, v56, v48
	v_fma_f32 v3, -v3, v52, v50
	v_div_fmas_f32 v3, v3, v48, v52
	v_lshlrev_b32_e32 v50, 16, v51
	v_and_b32_e32 v51, 0xffff0000, v51
	v_div_fixup_f32 v54, v3, v54, v39
	v_lshlrev_b32_e32 v3, 16, v53
	v_and_b32_e32 v39, 0xffff0000, v53
	v_pk_mul_f32 v[50:51], v[34:35], v[50:51] op_sel_hi:[0,1]
	v_mul_f32_e32 v48, 0xbfb8aa3b, v3
	v_pk_fma_f32 v[4:5], v[4:5], v[38:39], v[50:51] op_sel_hi:[1,0,1]
	v_lshlrev_b32_e32 v50, 16, v49
	v_and_b32_e32 v51, 0xffff0000, v49
	v_mul_f32_e32 v49, 0xbfb8aa3b, v39
	v_exp_f32_e32 v48, v48
	v_exp_f32_e32 v49, v49
	v_pk_fma_f32 v[4:5], v[2:3], v[50:51], v[4:5] op_sel_hi:[0,1,1]
	v_pk_mul_f32 v[36:37], v[36:37], v[54:55]
	v_pk_add_f32 v[48:49], v[48:49], 1.0 op_sel_hi:[1,0]
	s_nop 0
	v_div_scale_f32 v50, s[2:3], v49, v49, v39
	v_rcp_f32_e32 v51, v50
	v_cvt_pk_bf16_f32 v36, v36, v37
	v_fma_f32 v52, -v50, v51, 1.0
	v_fmac_f32_e32 v51, v52, v51
	v_div_scale_f32 v52, vcc, v39, v49, v39
	v_mul_f32_e32 v53, v52, v51
	v_fma_f32 v54, -v50, v53, v52
	v_fmac_f32_e32 v53, v54, v51
	v_fma_f32 v50, -v50, v53, v52
	v_div_fmas_f32 v50, v50, v51, v53
	v_div_fixup_f32 v49, v50, v49, v39
	v_div_scale_f32 v39, s[2:3], v48, v48, v3
	v_rcp_f32_e32 v50, v39
	s_nop 0
	v_fma_f32 v51, -v39, v50, 1.0
	v_fmac_f32_e32 v50, v51, v50
	v_div_scale_f32 v51, vcc, v3, v48, v3
	v_mul_f32_e32 v52, v51, v50
	v_fma_f32 v53, -v39, v52, v51
	v_fmac_f32_e32 v52, v53, v50
	v_fma_f32 v39, -v39, v52, v51
	v_div_fmas_f32 v39, v39, v50, v52
	v_div_fixup_f32 v48, v39, v48, v3
	v_pk_mul_f32 v[4:5], v[4:5], v[48:49]
	s_nop 0
	v_cvt_pk_bf16_f32 v37, v4, v5
	global_store_dwordx2 v[46:47], v[36:37], off
	global_load_dwordx2 v[36:37], v[40:41], off offset:16
	s_nop 0
	global_load_dwordx2 v[4:5], v[42:43], off offset:16
	global_load_dwordx2 v[48:49], v[46:47], off offset:16
	s_waitcnt vmcnt(2)
; DI unsigned pack2(float a, float b) { f32x2 v = {a, b}; bf16x2_t r = __builtin_convertvector(v, bf16x2_t); return __builtin_bit_cast(unsigned, r); }
; DI float bflo(unsigned v) { return __uint_as_float(v << 16); }
; DI float bfhi(unsigned v) { return __uint_as_float(v & 0xffff0000u); }
; DI float silu_f(float x) { return x / (1.f + __expf(-x)); }
; DI void nsa_slc_unit(const Params& p, int u, char* smem, bool probe = false) {
;     ...
;       const float a0 = (g0 * bflo(cv[0]) + g1 * o[dt][4 * g4] + g2 * bflo(wv[0])) * silu_f(bflo(gv[0]));
;       const float a1 = (g0 * bfhi(cv[0]) + g1 * o[dt][4 * g4 + 1] + g2 * bfhi(wv[0])) * silu_f(bfhi(gv[0]));
;       const float a2 = (g0 * bflo(cv[1]) + g1 * o[dt][4 * g4 + 2] + g2 * bflo(wv[1])) * silu_f(bflo(gv[1]));
;       const float a3 = (g0 * bfhi(cv[1]) + g1 * o[dt][4 * g4 + 3] + g2 * bfhi(wv[1])) * silu_f(bfhi(gv[1]));
;       *(u32x2*)gp = (u32x2){pack2(a0, a1), pack2(a2, a3)};
	v_lshlrev_b32_e32 v52, 16, v36
	v_and_b32_e32 v53, 0xffff0000, v36
	s_waitcnt vmcnt(0)
	v_lshlrev_b32_e32 v3, 16, v48
	v_and_b32_e32 v39, 0xffff0000, v48
	v_pk_mul_f32 v[52:53], v[34:35], v[52:53] op_sel_hi:[0,1]
	v_mul_f32_e32 v48, 0xbfb8aa3b, v3
	v_pk_fma_f32 v[6:7], v[6:7], v[38:39], v[52:53] op_sel_hi:[1,0,1]
	v_lshlrev_b32_e32 v52, 16, v4
	v_and_b32_e32 v53, 0xffff0000, v4
	v_mul_f32_e32 v4, 0xbfb8aa3b, v39
	v_exp_f32_e32 v50, v48
	v_exp_f32_e32 v51, v4
	v_pk_fma_f32 v[6:7], v[2:3], v[52:53], v[6:7] op_sel_hi:[0,1,1]
	v_pk_add_f32 v[50:51], v[50:51], 1.0 op_sel_hi:[1,0]
	s_nop 0
	v_div_scale_f32 v4, s[2:3], v51, v51, v39
	v_rcp_f32_e32 v36, v4
	s_nop 0
	v_fma_f32 v48, -v4, v36, 1.0
	v_fmac_f32_e32 v36, v48, v36
	v_div_scale_f32 v48, vcc, v39, v51, v39
	v_mul_f32_e32 v52, v48, v36
	v_fma_f32 v53, -v4, v52, v48
	v_fmac_f32_e32 v52, v53, v36
	v_fma_f32 v4, -v4, v52, v48
	v_div_fmas_f32 v4, v4, v36, v52
	v_div_fixup_f32 v51, v4, v51, v39
	v_div_scale_f32 v4, s[2:3], v50, v50, v3
	v_rcp_f32_e32 v36, v4
	s_nop 0
	v_fma_f32 v39, -v4, v36, 1.0
	v_fmac_f32_e32 v36, v39, v36
	v_div_scale_f32 v39, vcc, v3, v50, v3
	v_mul_f32_e32 v48, v39, v36
	v_fma_f32 v52, -v4, v48, v39
	v_fmac_f32_e32 v48, v52, v36
	v_fma_f32 v4, -v4, v48, v39
	v_div_fmas_f32 v4, v4, v36, v48
	v_lshlrev_b32_e32 v36, 16, v37
	v_and_b32_e32 v37, 0xffff0000, v37
	v_div_fixup_f32 v50, v4, v50, v3
	v_lshlrev_b32_e32 v3, 16, v49
	v_and_b32_e32 v39, 0xffff0000, v49
	v_pk_mul_f32 v[36:37], v[34:35], v[36:37] op_sel_hi:[0,1]
	v_mul_f32_e32 v4, 0xbfb8aa3b, v3
	v_pk_fma_f32 v[8:9], v[8:9], v[38:39], v[36:37] op_sel_hi:[1,0,1]
	v_lshlrev_b32_e32 v36, 16, v5
	v_and_b32_e32 v37, 0xffff0000, v5
	v_mul_f32_e32 v5, 0xbfb8aa3b, v39
	v_exp_f32_e32 v4, v4
	v_exp_f32_e32 v5, v5
	v_pk_fma_f32 v[8:9], v[2:3], v[36:37], v[8:9] op_sel_hi:[0,1,1]
	v_pk_mul_f32 v[6:7], v[6:7], v[50:51]
	v_pk_add_f32 v[4:5], v[4:5], 1.0 op_sel_hi:[1,0]
	s_nop 0
	v_div_scale_f32 v36, s[2:3], v5, v5, v39
	v_rcp_f32_e32 v37, v36
	v_cvt_pk_bf16_f32 v6, v6, v7
	v_fma_f32 v48, -v36, v37, 1.0
	v_fmac_f32_e32 v37, v48, v37
	v_div_scale_f32 v48, vcc, v39, v5, v39
	v_mul_f32_e32 v49, v48, v37
	v_fma_f32 v50, -v36, v49, v48
	v_fmac_f32_e32 v49, v50, v37
	v_fma_f32 v36, -v36, v49, v48
	v_div_fmas_f32 v36, v36, v37, v49
	v_div_fixup_f32 v5, v36, v5, v39
	v_div_scale_f32 v36, s[2:3], v4, v4, v3
	v_rcp_f32_e32 v37, v36
	s_nop 0
	v_fma_f32 v39, -v36, v37, 1.0
	v_fmac_f32_e32 v37, v39, v37
	v_div_scale_f32 v39, vcc, v3, v4, v3
	v_mul_f32_e32 v48, v39, v37
	v_fma_f32 v49, -v36, v48, v39
	v_fmac_f32_e32 v48, v49, v37
	v_fma_f32 v36, -v36, v48, v39
	v_div_fmas_f32 v36, v36, v37, v48
	v_div_fixup_f32 v4, v36, v4, v3
	v_pk_mul_f32 v[4:5], v[8:9], v[4:5]
	s_nop 0
	v_cvt_pk_bf16_f32 v7, v4, v5
	global_store_dwordx2 v[46:47], v[6:7], off offset:16
	global_load_dwordx2 v[6:7], v[40:41], off offset:32
	s_nop 0
	global_load_dwordx2 v[4:5], v[42:43], off offset:32
	global_load_dwordx2 v[8:9], v[46:47], off offset:32
	s_waitcnt vmcnt(2)
	v_lshlrev_b32_e32 v48, 16, v6
	v_and_b32_e32 v49, 0xffff0000, v6
	s_waitcnt vmcnt(0)
	v_lshlrev_b32_e32 v3, 16, v8
	v_and_b32_e32 v8, 0xffff0000, v8
	v_pk_mul_f32 v[48:49], v[34:35], v[48:49] op_sel_hi:[0,1]
	v_mul_f32_e32 v36, 0xbfb8aa3b, v3
	v_pk_fma_f32 v[10:11], v[10:11], v[38:39], v[48:49] op_sel_hi:[1,0,1]
	v_lshlrev_b32_e32 v48, 16, v4
	v_and_b32_e32 v49, 0xffff0000, v4
	v_mul_f32_e32 v4, 0xbfb8aa3b, v8
	v_exp_f32_e32 v36, v36
	v_exp_f32_e32 v37, v4
	v_pk_fma_f32 v[10:11], v[2:3], v[48:49], v[10:11] op_sel_hi:[0,1,1]
	v_pk_add_f32 v[36:37], v[36:37], 1.0 op_sel_hi:[1,0]
	s_nop 0
	v_div_scale_f32 v4, s[2:3], v37, v37, v8
	v_rcp_f32_e32 v6, v4
	s_nop 0
	v_fma_f32 v39, -v4, v6, 1.0
	v_fmac_f32_e32 v6, v39, v6
	v_div_scale_f32 v39, vcc, v8, v37, v8
	v_mul_f32_e32 v48, v39, v6
	v_fma_f32 v49, -v4, v48, v39
	v_fmac_f32_e32 v48, v49, v6
	v_fma_f32 v4, -v4, v48, v39
	v_div_fmas_f32 v4, v4, v6, v48
	v_div_fixup_f32 v37, v4, v37, v8
	v_div_scale_f32 v4, s[2:3], v36, v36, v3
	v_rcp_f32_e32 v6, v4
	s_nop 0
	v_fma_f32 v8, -v4, v6, 1.0
	v_fmac_f32_e32 v6, v8, v6
	v_div_scale_f32 v8, vcc, v3, v36, v3
	v_mul_f32_e32 v39, v8, v6
	v_fma_f32 v48, -v4, v39, v8
	v_fmac_f32_e32 v39, v48, v6
	v_fma_f32 v4, -v4, v39, v8
	v_div_fmas_f32 v4, v4, v6, v39
	v_div_fixup_f32 v36, v4, v36, v3
	v_pk_mul_f32 v[10:11], v[10:11], v[36:37]
	v_lshlrev_b32_e32 v3, 16, v9
	v_and_b32_e32 v36, 0xffff0000, v9
	v_mul_f32_e32 v4, 0xbfb8aa3b, v3
	v_lshlrev_b32_e32 v8, 16, v5
	v_and_b32_e32 v9, 0xffff0000, v5
	v_mul_f32_e32 v5, 0xbfb8aa3b, v36
	v_exp_f32_e32 v4, v4
	v_exp_f32_e32 v5, v5
	v_lshlrev_b32_e32 v6, 16, v7
	v_and_b32_e32 v7, 0xffff0000, v7
	v_pk_mul_f32 v[6:7], v[34:35], v[6:7] op_sel_hi:[0,1]
	v_pk_fma_f32 v[6:7], v[12:13], v[38:39], v[6:7] op_sel_hi:[1,0,1]
	v_pk_add_f32 v[4:5], v[4:5], 1.0 op_sel_hi:[1,0]
	v_pk_fma_f32 v[6:7], v[2:3], v[8:9], v[6:7] op_sel_hi:[0,1,1]
	v_div_scale_f32 v8, s[2:3], v5, v5, v36
	v_rcp_f32_e32 v9, v8
	s_nop 0
	v_fma_f32 v12, -v8, v9, 1.0
	v_fmac_f32_e32 v9, v12, v9
	v_div_scale_f32 v12, vcc, v36, v5, v36
	v_mul_f32_e32 v13, v12, v9
	v_fma_f32 v37, -v8, v13, v12
	v_fmac_f32_e32 v13, v37, v9
	v_fma_f32 v8, -v8, v13, v12
	v_div_fmas_f32 v8, v8, v9, v13
	v_div_fixup_f32 v5, v8, v5, v36
	v_div_scale_f32 v8, s[2:3], v4, v4, v3
	v_rcp_f32_e32 v9, v8
	s_nop 0
	v_fma_f32 v12, -v8, v9, 1.0
	v_fmac_f32_e32 v9, v12, v9
	v_div_scale_f32 v12, vcc, v3, v4, v3
	v_mul_f32_e32 v13, v12, v9
	v_fma_f32 v36, -v8, v13, v12
	v_fmac_f32_e32 v13, v36, v9
	v_fma_f32 v8, -v8, v13, v12
	v_div_fmas_f32 v8, v8, v9, v13
	v_div_fixup_f32 v4, v8, v4, v3
	v_pk_mul_f32 v[4:5], v[6:7], v[4:5]
	v_cvt_pk_bf16_f32 v6, v10, v11
	v_cvt_pk_bf16_f32 v7, v4, v5
	global_store_dwordx2 v[46:47], v[6:7], off offset:32
	global_load_dwordx2 v[6:7], v[40:41], off offset:48
	s_nop 0
	global_load_dwordx2 v[4:5], v[42:43], off offset:48
	global_load_dwordx2 v[8:9], v[46:47], off offset:48
	s_waitcnt vmcnt(2)
; DI unsigned pack2(float a, float b) { f32x2 v = {a, b}; bf16x2_t r = __builtin_convertvector(v, bf16x2_t); return __builtin_bit_cast(unsigned, r); }
; DI float bflo(unsigned v) { return __uint_as_float(v << 16); }
; DI float bfhi(unsigned v) { return __uint_as_float(v & 0xffff0000u); }
; DI size_t blk(size_t row, int k, int R) { return ((size_t)(k >> 5) * R + row) * 32 + (k & 31); }
; DI float silu_f(float x) { return x / (1.f + __expf(-x)); }
; DI void nsa_slc_unit(const Params& p, int u, char* smem, bool probe = false) {
;     ...
;       const int d = 32 * dt + 8 * g4 + 4 * h;
;       bf16_t* gp = p.G + blk(tok, head * 64 + d, NTOK);
;       const u32x2 cv = *(const u32x2*)(oc + d), wv = *(const u32x2*)(ow + d), gv = *(const u32x2*)gp;
;       const float a0 = (g0 * bflo(cv[0]) + g1 * o[dt][4 * g4] + g2 * bflo(wv[0])) * silu_f(bflo(gv[0]));
;       const float a1 = (g0 * bfhi(cv[0]) + g1 * o[dt][4 * g4 + 1] + g2 * bfhi(wv[0])) * silu_f(bfhi(gv[0]));
;       const float a2 = (g0 * bflo(cv[1]) + g1 * o[dt][4 * g4 + 2] + g2 * bflo(wv[1])) * silu_f(bflo(gv[1]));
;       const float a3 = (g0 * bfhi(cv[1]) + g1 * o[dt][4 * g4 + 3] + g2 * bfhi(wv[1])) * silu_f(bfhi(gv[1]));
;       *(u32x2*)gp = (u32x2){pack2(a0, a1), pack2(a2, a3)};
	v_lshlrev_b32_e32 v12, 16, v6
	v_and_b32_e32 v13, 0xffff0000, v6
	s_waitcnt vmcnt(0)
	v_lshlrev_b32_e32 v3, 16, v8
	v_and_b32_e32 v8, 0xffff0000, v8
	v_pk_mul_f32 v[12:13], v[34:35], v[12:13] op_sel_hi:[0,1]
	v_mul_f32_e32 v10, 0xbfb8aa3b, v3
	v_pk_fma_f32 v[12:13], v[14:15], v[38:39], v[12:13] op_sel_hi:[1,0,1]
	v_lshlrev_b32_e32 v14, 16, v4
	v_and_b32_e32 v15, 0xffff0000, v4
	v_mul_f32_e32 v4, 0xbfb8aa3b, v8
	v_exp_f32_e32 v10, v10
	v_exp_f32_e32 v11, v4
	v_pk_fma_f32 v[12:13], v[2:3], v[14:15], v[12:13] op_sel_hi:[0,1,1]
	v_pk_add_f32 v[10:11], v[10:11], 1.0 op_sel_hi:[1,0]
	s_nop 0
	v_div_scale_f32 v4, s[2:3], v11, v11, v8
	v_rcp_f32_e32 v6, v4
	s_nop 0
	v_fma_f32 v14, -v4, v6, 1.0
	v_fmac_f32_e32 v6, v14, v6
	v_div_scale_f32 v14, vcc, v8, v11, v8
	v_mul_f32_e32 v15, v14, v6
	v_fma_f32 v36, -v4, v15, v14
	v_fmac_f32_e32 v15, v36, v6
	v_fma_f32 v4, -v4, v15, v14
	v_div_fmas_f32 v4, v4, v6, v15
	v_div_fixup_f32 v11, v4, v11, v8
	v_div_scale_f32 v4, s[2:3], v10, v10, v3
	v_rcp_f32_e32 v6, v4
	s_nop 0
	v_fma_f32 v8, -v4, v6, 1.0
	v_fmac_f32_e32 v6, v8, v6
	v_div_scale_f32 v8, vcc, v3, v10, v3
	v_mul_f32_e32 v14, v8, v6
	v_fma_f32 v15, -v4, v14, v8
	v_fmac_f32_e32 v14, v15, v6
	v_fma_f32 v4, -v4, v14, v8
	v_div_fmas_f32 v4, v4, v6, v14
	v_div_fixup_f32 v10, v4, v10, v3
	v_pk_mul_f32 v[10:11], v[12:13], v[10:11]
	v_lshlrev_b32_e32 v3, 16, v9
	v_and_b32_e32 v12, 0xffff0000, v9
	v_mul_f32_e32 v4, 0xbfb8aa3b, v3
	v_lshlrev_b32_e32 v8, 16, v5
	v_and_b32_e32 v9, 0xffff0000, v5
	v_mul_f32_e32 v5, 0xbfb8aa3b, v12
	v_exp_f32_e32 v4, v4
	v_exp_f32_e32 v5, v5
	v_lshlrev_b32_e32 v6, 16, v7
	v_and_b32_e32 v7, 0xffff0000, v7
	v_pk_mul_f32 v[6:7], v[34:35], v[6:7] op_sel_hi:[0,1]
	v_pk_fma_f32 v[6:7], v[16:17], v[38:39], v[6:7] op_sel_hi:[1,0,1]
	v_pk_add_f32 v[4:5], v[4:5], 1.0 op_sel_hi:[1,0]
	v_pk_fma_f32 v[6:7], v[2:3], v[8:9], v[6:7] op_sel_hi:[0,1,1]
	v_div_scale_f32 v8, s[2:3], v5, v5, v12
	v_rcp_f32_e32 v9, v8
	s_nop 0
	v_fma_f32 v13, -v8, v9, 1.0
	v_fmac_f32_e32 v9, v13, v9
	v_div_scale_f32 v13, vcc, v12, v5, v12
	v_mul_f32_e32 v14, v13, v9
	v_fma_f32 v15, -v8, v14, v13
	v_fmac_f32_e32 v14, v15, v9
	v_fma_f32 v8, -v8, v14, v13
	v_div_fmas_f32 v8, v8, v9, v14
	v_div_fixup_f32 v5, v8, v5, v12
	v_div_scale_f32 v8, s[2:3], v4, v4, v3
	v_rcp_f32_e32 v9, v8
	s_nop 0
	v_fma_f32 v12, -v8, v9, 1.0
	v_fmac_f32_e32 v9, v12, v9
	v_div_scale_f32 v12, vcc, v3, v4, v3
	v_mul_f32_e32 v13, v12, v9
	v_fma_f32 v14, -v8, v13, v12
	v_fmac_f32_e32 v13, v14, v9
	v_fma_f32 v8, -v8, v13, v12
	v_div_fmas_f32 v8, v8, v9, v13
	v_div_fixup_f32 v4, v8, v4, v3
	v_pk_mul_f32 v[4:5], v[6:7], v[4:5]
	v_cvt_pk_bf16_f32 v6, v10, v11
	v_cvt_pk_bf16_f32 v7, v4, v5
	v_lshl_add_u64 v[4:5], v[180:181], 0, v[0:1]
	v_lshlrev_b64 v[4:5], 6, v[4:5]
	global_store_dwordx2 v[46:47], v[6:7], off offset:48
	v_lshl_add_u64 v[4:5], s[38:39], 0, v[4:5]
	v_lshl_add_u64 v[4:5], v[4:5], 0, v[44:45]
	global_load_dwordx2 v[6:7], v[40:41], off offset:64
	global_load_dwordx2 v[8:9], v[42:43], off offset:64
	global_load_dwordx2 v[10:11], v[4:5], off
	s_waitcnt vmcnt(2)
	v_lshlrev_b32_e32 v14, 16, v6
	v_and_b32_e32 v15, 0xffff0000, v6
	s_waitcnt vmcnt(0)
	v_lshlrev_b32_e32 v0, 16, v10
	v_and_b32_e32 v3, 0xffff0000, v10
	v_mul_f32_e32 v10, 0xbfb8aa3b, v0
	v_mul_f32_e32 v6, 0xbfb8aa3b, v3
	v_exp_f32_e32 v12, v10
	v_exp_f32_e32 v13, v6
	v_lshlrev_b32_e32 v16, 16, v8
	v_and_b32_e32 v17, 0xffff0000, v8
	v_pk_mul_f32 v[14:15], v[34:35], v[14:15] op_sel_hi:[0,1]
	v_pk_add_f32 v[12:13], v[12:13], 1.0 op_sel_hi:[1,0]
	v_pk_fma_f32 v[14:15], v[18:19], v[38:39], v[14:15] op_sel_hi:[1,0,1]
	v_div_scale_f32 v6, s[2:3], v13, v13, v3
	v_rcp_f32_e32 v8, v6
	v_pk_fma_f32 v[14:15], v[2:3], v[16:17], v[14:15] op_sel_hi:[0,1,1]
	v_fma_f32 v10, -v6, v8, 1.0
	v_fmac_f32_e32 v8, v10, v8
	v_div_scale_f32 v10, vcc, v3, v13, v3
	v_mul_f32_e32 v16, v10, v8
	v_fma_f32 v17, -v6, v16, v10
	v_fmac_f32_e32 v16, v17, v8
	v_fma_f32 v6, -v6, v16, v10
	v_div_fmas_f32 v6, v6, v8, v16
	v_div_fixup_f32 v13, v6, v13, v3
	v_div_scale_f32 v3, s[2:3], v12, v12, v0
	v_rcp_f32_e32 v6, v3
	s_nop 0
	v_fma_f32 v8, -v3, v6, 1.0
	v_fmac_f32_e32 v6, v8, v6
	v_div_scale_f32 v8, vcc, v0, v12, v0
	v_mul_f32_e32 v10, v8, v6
	v_fma_f32 v16, -v3, v10, v8
	v_fmac_f32_e32 v10, v16, v6
	v_fma_f32 v3, -v3, v10, v8
	v_div_fmas_f32 v3, v3, v6, v10
	v_div_fixup_f32 v12, v3, v12, v0
	v_lshlrev_b32_e32 v0, 16, v11
	v_and_b32_e32 v3, 0xffff0000, v11
	v_mul_f32_e32 v6, 0xbfb8aa3b, v0
	v_lshlrev_b32_e32 v10, 16, v7
	v_and_b32_e32 v11, 0xffff0000, v7
	v_mul_f32_e32 v7, 0xbfb8aa3b, v3
	v_exp_f32_e32 v6, v6
	v_exp_f32_e32 v7, v7
	v_pk_mul_f32 v[10:11], v[34:35], v[10:11] op_sel_hi:[0,1]
	v_pk_fma_f32 v[10:11], v[20:21], v[38:39], v[10:11] op_sel_hi:[1,0,1]
	v_lshlrev_b32_e32 v8, 16, v9
	v_and_b32_e32 v9, 0xffff0000, v9
	v_pk_add_f32 v[6:7], v[6:7], 1.0 op_sel_hi:[1,0]
	v_pk_fma_f32 v[8:9], v[2:3], v[8:9], v[10:11] op_sel_hi:[0,1,1]
	v_div_scale_f32 v10, s[2:3], v7, v7, v3
	v_rcp_f32_e32 v11, v10
	v_pk_mul_f32 v[12:13], v[14:15], v[12:13]
	v_fma_f32 v14, -v10, v11, 1.0
	v_fmac_f32_e32 v11, v14, v11
	v_div_scale_f32 v14, vcc, v3, v7, v3
	v_mul_f32_e32 v15, v14, v11
	v_fma_f32 v16, -v10, v15, v14
	v_fmac_f32_e32 v15, v16, v11
	v_fma_f32 v10, -v10, v15, v14
	v_div_fmas_f32 v10, v10, v11, v15
	v_div_fixup_f32 v7, v10, v7, v3
	v_div_scale_f32 v3, s[2:3], v6, v6, v0
	v_rcp_f32_e32 v10, v3
	s_nop 0
	v_fma_f32 v11, -v3, v10, 1.0
	v_fmac_f32_e32 v10, v11, v10
	v_div_scale_f32 v11, vcc, v0, v6, v0
	v_mul_f32_e32 v14, v11, v10
	v_fma_f32 v15, -v3, v14, v11
	v_fmac_f32_e32 v14, v15, v10
	v_fma_f32 v3, -v3, v14, v11
	v_div_fmas_f32 v3, v3, v10, v14
	v_div_fixup_f32 v6, v3, v6, v0
	v_pk_mul_f32 v[6:7], v[8:9], v[6:7]
	v_cvt_pk_bf16_f32 v8, v12, v13
	v_cvt_pk_bf16_f32 v9, v6, v7
	global_store_dwordx2 v[4:5], v[8:9], off
	global_load_dwordx2 v[8:9], v[40:41], off offset:80
	s_nop 0
	global_load_dwordx2 v[6:7], v[42:43], off offset:80
	global_load_dwordx2 v[10:11], v[4:5], off offset:16
	s_waitcnt vmcnt(2)
; DI unsigned pack2(float a, float b) { f32x2 v = {a, b}; bf16x2_t r = __builtin_convertvector(v, bf16x2_t); return __builtin_bit_cast(unsigned, r); }
; DI float bflo(unsigned v) { return __uint_as_float(v << 16); }
; DI float bfhi(unsigned v) { return __uint_as_float(v & 0xffff0000u); }
; DI float silu_f(float x) { return x / (1.f + __expf(-x)); }
; DI void nsa_slc_unit(const Params& p, int u, char* smem, bool probe = false) {
;     ...
;       const float a0 = (g0 * bflo(cv[0]) + g1 * o[dt][4 * g4] + g2 * bflo(wv[0])) * silu_f(bflo(gv[0]));
;       const float a1 = (g0 * bfhi(cv[0]) + g1 * o[dt][4 * g4 + 1] + g2 * bfhi(wv[0])) * silu_f(bfhi(gv[0]));
;       const float a2 = (g0 * bflo(cv[1]) + g1 * o[dt][4 * g4 + 2] + g2 * bflo(wv[1])) * silu_f(bflo(gv[1]));
;       const float a3 = (g0 * bfhi(cv[1]) + g1 * o[dt][4 * g4 + 3] + g2 * bfhi(wv[1])) * silu_f(bfhi(gv[1]));
;       *(u32x2*)gp = (u32x2){pack2(a0, a1), pack2(a2, a3)};
	v_lshlrev_b32_e32 v14, 16, v8
	s_waitcnt vmcnt(1)
	v_lshlrev_b32_e32 v16, 16, v6
	s_waitcnt vmcnt(0)
	v_lshlrev_b32_e32 v0, 16, v10
	v_and_b32_e32 v3, 0xffff0000, v10
	v_mul_f32_e32 v10, 0xbfb8aa3b, v0
	v_and_b32_e32 v17, 0xffff0000, v6
	v_mul_f32_e32 v6, 0xbfb8aa3b, v3
	v_exp_f32_e32 v12, v10
	v_exp_f32_e32 v13, v6
	v_and_b32_e32 v15, 0xffff0000, v8
	v_pk_mul_f32 v[14:15], v[34:35], v[14:15] op_sel_hi:[0,1]
	v_pk_fma_f32 v[14:15], v[22:23], v[38:39], v[14:15] op_sel_hi:[1,0,1]
	v_pk_add_f32 v[12:13], v[12:13], 1.0 op_sel_hi:[1,0]
	v_pk_fma_f32 v[14:15], v[2:3], v[16:17], v[14:15] op_sel_hi:[0,1,1]
	v_div_scale_f32 v6, s[2:3], v13, v13, v3
	v_rcp_f32_e32 v8, v6
	s_nop 0
	v_fma_f32 v10, -v6, v8, 1.0
	v_fmac_f32_e32 v8, v10, v8
	v_div_scale_f32 v10, vcc, v3, v13, v3
	v_mul_f32_e32 v16, v10, v8
	v_fma_f32 v17, -v6, v16, v10
	v_fmac_f32_e32 v16, v17, v8
	v_fma_f32 v6, -v6, v16, v10
	v_div_fmas_f32 v6, v6, v8, v16
	v_div_fixup_f32 v13, v6, v13, v3
	v_div_scale_f32 v3, s[2:3], v12, v12, v0
	v_rcp_f32_e32 v6, v3
	s_nop 0
	v_fma_f32 v8, -v3, v6, 1.0
	v_fmac_f32_e32 v6, v8, v6
	v_div_scale_f32 v8, vcc, v0, v12, v0
	v_mul_f32_e32 v10, v8, v6
	v_fma_f32 v16, -v3, v10, v8
	v_fmac_f32_e32 v10, v16, v6
	v_fma_f32 v3, -v3, v10, v8
	v_div_fmas_f32 v3, v3, v6, v10
	v_div_fixup_f32 v12, v3, v12, v0
	v_lshlrev_b32_e32 v0, 16, v11
	v_and_b32_e32 v3, 0xffff0000, v11
	v_mul_f32_e32 v6, 0xbfb8aa3b, v0
	v_lshlrev_b32_e32 v10, 16, v7
	v_and_b32_e32 v11, 0xffff0000, v7
	v_mul_f32_e32 v7, 0xbfb8aa3b, v3
	v_exp_f32_e32 v6, v6
	v_exp_f32_e32 v7, v7
	v_lshlrev_b32_e32 v8, 16, v9
	v_and_b32_e32 v9, 0xffff0000, v9
	v_pk_mul_f32 v[8:9], v[34:35], v[8:9] op_sel_hi:[0,1]
	v_pk_fma_f32 v[8:9], v[24:25], v[38:39], v[8:9] op_sel_hi:[1,0,1]
	v_pk_add_f32 v[6:7], v[6:7], 1.0 op_sel_hi:[1,0]
	v_pk_fma_f32 v[8:9], v[2:3], v[10:11], v[8:9] op_sel_hi:[0,1,1]
	v_div_scale_f32 v10, s[2:3], v7, v7, v3
	v_rcp_f32_e32 v11, v10
	v_pk_mul_f32 v[12:13], v[14:15], v[12:13]
	v_fma_f32 v14, -v10, v11, 1.0
	v_fmac_f32_e32 v11, v14, v11
	v_div_scale_f32 v14, vcc, v3, v7, v3
	v_mul_f32_e32 v15, v14, v11
	v_fma_f32 v16, -v10, v15, v14
	v_fmac_f32_e32 v15, v16, v11
	v_fma_f32 v10, -v10, v15, v14
	v_div_fmas_f32 v10, v10, v11, v15
	v_div_fixup_f32 v7, v10, v7, v3
	v_div_scale_f32 v3, s[2:3], v6, v6, v0
	v_rcp_f32_e32 v10, v3
	s_nop 0
	v_fma_f32 v11, -v3, v10, 1.0
	v_fmac_f32_e32 v10, v11, v10
	v_div_scale_f32 v11, vcc, v0, v6, v0
	v_mul_f32_e32 v14, v11, v10
	v_fma_f32 v15, -v3, v14, v11
	v_fmac_f32_e32 v14, v15, v10
	v_fma_f32 v3, -v3, v14, v11
	v_div_fmas_f32 v3, v3, v10, v14
	v_div_fixup_f32 v6, v3, v6, v0
	v_pk_mul_f32 v[6:7], v[8:9], v[6:7]
	v_cvt_pk_bf16_f32 v8, v12, v13
	v_cvt_pk_bf16_f32 v9, v6, v7
	global_store_dwordx2 v[4:5], v[8:9], off offset:16
	global_load_dwordx2 v[8:9], v[40:41], off offset:96
	s_nop 0
	global_load_dwordx2 v[6:7], v[42:43], off offset:96
	global_load_dwordx2 v[10:11], v[4:5], off offset:32
	s_waitcnt vmcnt(2)
	v_lshlrev_b32_e32 v14, 16, v8
	s_waitcnt vmcnt(1)
	v_lshlrev_b32_e32 v16, 16, v6
	s_waitcnt vmcnt(0)
; DI unsigned pack2(float a, float b) { f32x2 v = {a, b}; bf16x2_t r = __builtin_convertvector(v, bf16x2_t); return __builtin_bit_cast(unsigned, r); }
; DI float bflo(unsigned v) { return __uint_as_float(v << 16); }
; DI float bfhi(unsigned v) { return __uint_as_float(v & 0xffff0000u); }
; DI float silu_f(float x) { return x / (1.f + __expf(-x)); }
; DI void nsa_slc_unit(const Params& p, int u, char* smem, bool probe = false) {
;     ...
;       const float a0 = (g0 * bflo(cv[0]) + g1 * o[dt][4 * g4] + g2 * bflo(wv[0])) * silu_f(bflo(gv[0]));
;       const float a1 = (g0 * bfhi(cv[0]) + g1 * o[dt][4 * g4 + 1] + g2 * bfhi(wv[0])) * silu_f(bfhi(gv[0]));
;       const float a2 = (g0 * bflo(cv[1]) + g1 * o[dt][4 * g4 + 2] + g2 * bflo(wv[1])) * silu_f(bflo(gv[1]));
;       const float a3 = (g0 * bfhi(cv[1]) + g1 * o[dt][4 * g4 + 3] + g2 * bfhi(wv[1])) * silu_f(bfhi(gv[1]));
;       *(u32x2*)gp = (u32x2){pack2(a0, a1), pack2(a2, a3)};
	v_lshlrev_b32_e32 v0, 16, v10
	v_and_b32_e32 v3, 0xffff0000, v10
	v_mul_f32_e32 v10, 0xbfb8aa3b, v0
	v_and_b32_e32 v17, 0xffff0000, v6
	v_mul_f32_e32 v6, 0xbfb8aa3b, v3
	v_exp_f32_e32 v12, v10
	v_exp_f32_e32 v13, v6
	v_and_b32_e32 v15, 0xffff0000, v8
	v_pk_mul_f32 v[14:15], v[34:35], v[14:15] op_sel_hi:[0,1]
	v_pk_fma_f32 v[14:15], v[26:27], v[38:39], v[14:15] op_sel_hi:[1,0,1]
	v_pk_add_f32 v[12:13], v[12:13], 1.0 op_sel_hi:[1,0]
	v_pk_fma_f32 v[14:15], v[2:3], v[16:17], v[14:15] op_sel_hi:[0,1,1]
	v_div_scale_f32 v6, s[2:3], v13, v13, v3
	v_rcp_f32_e32 v8, v6
	s_nop 0
	v_fma_f32 v10, -v6, v8, 1.0
	v_fmac_f32_e32 v8, v10, v8
	v_div_scale_f32 v10, vcc, v3, v13, v3
	v_mul_f32_e32 v16, v10, v8
	v_fma_f32 v17, -v6, v16, v10
	v_fmac_f32_e32 v16, v17, v8
	v_fma_f32 v6, -v6, v16, v10
	v_div_fmas_f32 v6, v6, v8, v16
	v_div_fixup_f32 v13, v6, v13, v3
	v_div_scale_f32 v3, s[2:3], v12, v12, v0
	v_rcp_f32_e32 v6, v3
	s_nop 0
	v_fma_f32 v8, -v3, v6, 1.0
	v_fmac_f32_e32 v6, v8, v6
	v_div_scale_f32 v8, vcc, v0, v12, v0
	v_mul_f32_e32 v10, v8, v6
	v_fma_f32 v16, -v3, v10, v8
	v_fmac_f32_e32 v10, v16, v6
	v_fma_f32 v3, -v3, v10, v8
	v_div_fmas_f32 v3, v3, v6, v10
	v_div_fixup_f32 v12, v3, v12, v0
	v_lshlrev_b32_e32 v0, 16, v11
	v_and_b32_e32 v3, 0xffff0000, v11
	v_mul_f32_e32 v6, 0xbfb8aa3b, v0
	v_lshlrev_b32_e32 v10, 16, v7
	v_and_b32_e32 v11, 0xffff0000, v7
	v_mul_f32_e32 v7, 0xbfb8aa3b, v3
	v_exp_f32_e32 v6, v6
	v_exp_f32_e32 v7, v7
	v_lshlrev_b32_e32 v8, 16, v9
	v_and_b32_e32 v9, 0xffff0000, v9
	v_pk_mul_f32 v[8:9], v[34:35], v[8:9] op_sel_hi:[0,1]
	v_pk_fma_f32 v[8:9], v[28:29], v[38:39], v[8:9] op_sel_hi:[1,0,1]
	v_pk_add_f32 v[6:7], v[6:7], 1.0 op_sel_hi:[1,0]
	v_pk_fma_f32 v[8:9], v[2:3], v[10:11], v[8:9] op_sel_hi:[0,1,1]
	v_div_scale_f32 v10, s[2:3], v7, v7, v3
	v_rcp_f32_e32 v11, v10
	v_pk_mul_f32 v[12:13], v[14:15], v[12:13]
	v_fma_f32 v14, -v10, v11, 1.0
	v_fmac_f32_e32 v11, v14, v11
	v_div_scale_f32 v14, vcc, v3, v7, v3
	v_mul_f32_e32 v15, v14, v11
	v_fma_f32 v16, -v10, v15, v14
	v_fmac_f32_e32 v15, v16, v11
	v_fma_f32 v10, -v10, v15, v14
	v_div_fmas_f32 v10, v10, v11, v15
	v_div_fixup_f32 v7, v10, v7, v3
	v_div_scale_f32 v3, s[2:3], v6, v6, v0
	v_rcp_f32_e32 v10, v3
	s_nop 0
	v_fma_f32 v11, -v3, v10, 1.0
	v_fmac_f32_e32 v10, v11, v10
	v_div_scale_f32 v11, vcc, v0, v6, v0
	v_mul_f32_e32 v14, v11, v10
	v_fma_f32 v15, -v3, v14, v11
	v_fmac_f32_e32 v14, v15, v10
	v_fma_f32 v3, -v3, v14, v11
	v_div_fmas_f32 v3, v3, v10, v14
	v_div_fixup_f32 v6, v3, v6, v0
	v_pk_mul_f32 v[6:7], v[8:9], v[6:7]
	v_cvt_pk_bf16_f32 v8, v12, v13
	v_cvt_pk_bf16_f32 v9, v6, v7
	global_store_dwordx2 v[4:5], v[8:9], off offset:32
	global_load_dwordx2 v[8:9], v[40:41], off offset:112
	s_nop 0
	global_load_dwordx2 v[6:7], v[42:43], off offset:112
	global_load_dwordx2 v[10:11], v[4:5], off offset:48
	s_waitcnt vmcnt(2)
	v_lshlrev_b32_e32 v14, 16, v8
	s_waitcnt vmcnt(1)
	v_lshlrev_b32_e32 v16, 16, v6
	s_waitcnt vmcnt(0)
	v_lshlrev_b32_e32 v0, 16, v10
	v_and_b32_e32 v3, 0xffff0000, v10
	v_mul_f32_e32 v10, 0xbfb8aa3b, v0
	v_and_b32_e32 v17, 0xffff0000, v6
	v_mul_f32_e32 v6, 0xbfb8aa3b, v3
	v_exp_f32_e32 v12, v10
	v_exp_f32_e32 v13, v6
	v_and_b32_e32 v15, 0xffff0000, v8
	v_pk_mul_f32 v[14:15], v[34:35], v[14:15] op_sel_hi:[0,1]
	v_pk_fma_f32 v[14:15], v[30:31], v[38:39], v[14:15] op_sel_hi:[1,0,1]
	v_pk_add_f32 v[12:13], v[12:13], 1.0 op_sel_hi:[1,0]
	v_pk_fma_f32 v[14:15], v[2:3], v[16:17], v[14:15] op_sel_hi:[0,1,1]
	v_div_scale_f32 v6, s[2:3], v13, v13, v3
	v_rcp_f32_e32 v8, v6
	s_nop 0
	v_fma_f32 v10, -v6, v8, 1.0
	v_fmac_f32_e32 v8, v10, v8
	v_div_scale_f32 v10, vcc, v3, v13, v3
	v_mul_f32_e32 v16, v10, v8
	v_fma_f32 v17, -v6, v16, v10
	v_fmac_f32_e32 v16, v17, v8
	v_fma_f32 v6, -v6, v16, v10
	v_div_fmas_f32 v6, v6, v8, v16
	v_div_fixup_f32 v13, v6, v13, v3
	v_div_scale_f32 v3, s[2:3], v12, v12, v0
	v_rcp_f32_e32 v6, v3
	s_nop 0
	v_fma_f32 v8, -v3, v6, 1.0
	v_fmac_f32_e32 v6, v8, v6
	v_div_scale_f32 v8, vcc, v0, v12, v0
	v_mul_f32_e32 v10, v8, v6
	v_fma_f32 v16, -v3, v10, v8
	v_fmac_f32_e32 v10, v16, v6
	v_fma_f32 v3, -v3, v10, v8
	v_div_fmas_f32 v3, v3, v6, v10
	v_div_fixup_f32 v12, v3, v12, v0
	v_pk_mul_f32 v[12:13], v[14:15], v[12:13]
	v_lshlrev_b32_e32 v0, 16, v11
	v_and_b32_e32 v14, 0xffff0000, v11
	v_mul_f32_e32 v3, 0xbfb8aa3b, v0
	v_lshlrev_b32_e32 v10, 16, v7
	v_and_b32_e32 v11, 0xffff0000, v7
	v_mul_f32_e32 v7, 0xbfb8aa3b, v14
	v_exp_f32_e32 v6, v3
	v_exp_f32_e32 v7, v7
	v_lshlrev_b32_e32 v8, 16, v9
	v_and_b32_e32 v9, 0xffff0000, v9
	v_pk_mul_f32 v[8:9], v[34:35], v[8:9] op_sel_hi:[0,1]
	v_pk_fma_f32 v[8:9], v[32:33], v[38:39], v[8:9] op_sel_hi:[1,0,1]
	v_pk_add_f32 v[6:7], v[6:7], 1.0 op_sel_hi:[1,0]
	v_pk_fma_f32 v[2:3], v[2:3], v[10:11], v[8:9] op_sel_hi:[0,1,1]
	v_div_scale_f32 v8, s[2:3], v7, v7, v14
	v_rcp_f32_e32 v9, v8
	s_nop 0
	v_fma_f32 v10, -v8, v9, 1.0
	v_fmac_f32_e32 v9, v10, v9
	v_div_scale_f32 v10, vcc, v14, v7, v14
	v_mul_f32_e32 v11, v10, v9
	v_fma_f32 v15, -v8, v11, v10
	v_fmac_f32_e32 v11, v15, v9
	v_fma_f32 v8, -v8, v11, v10
	v_div_fmas_f32 v8, v8, v9, v11
	v_div_fixup_f32 v7, v8, v7, v14
	v_div_scale_f32 v8, s[2:3], v6, v6, v0
	v_rcp_f32_e32 v9, v8
	s_nop 0
	v_fma_f32 v10, -v8, v9, 1.0
	v_fmac_f32_e32 v9, v10, v9
	v_div_scale_f32 v10, vcc, v0, v6, v0
	v_mul_f32_e32 v11, v10, v9
	v_fma_f32 v14, -v8, v11, v10
	v_fmac_f32_e32 v11, v14, v9
	v_fma_f32 v8, -v8, v11, v10
	v_div_fmas_f32 v8, v8, v9, v11
	v_div_fixup_f32 v6, v8, v6, v0
	v_pk_mul_f32 v[2:3], v[2:3], v[6:7]
	v_cvt_pk_bf16_f32 v6, v12, v13
	v_cvt_pk_bf16_f32 v7, v2, v3
	global_store_dwordx2 v[4:5], v[6:7], off offset:48
	s_cbranch_scc0 .LBB0_729

; DI int otid() { int t = threadIdx.x; asm volatile("" : "+v"(t)); return t; }
; DI void nsa_slc_unit(const Params& p, int u, char* smem, bool probe = false) {
;   const int tid = otid(), lane = tid & 63, w = __builtin_amdgcn_readfirstlane(tid >> 6), r = lane & 31, h = lane >> 5;
;   const int chunk = u & 255, g = (u >> 8) & 1, b = u >> 9;
;   const int q0 = 16 * chunk, qi = r >> 3, hd = r & 7, tq = q0 + 4 * w + qi, head = 8 * g + hd; const size_t tok = (size_t)b * SEQ + tq;
;   __syncthreads();
;   const ull* sm = p.selmask + (size_t)(b * 2 + g) * SEQ + q0;
; __global__ void __launch_bounds__(256, 2) mega_kernel(Params p) {
;     ...
;         const int v = balance_unit(u, G), ch = 255 - (v >> 4), gb = v & 15;
;         nsa_slc_unit(p, ((gb >> 1) << 9) | ((gb & 1) << 8) | ch, smem);
.LBB0_815:
	s_ashr_i32 s3, s2, 4
	s_lshl_b32 s2, s2, 8
	s_sub_i32 s3, 0xff, s3
	s_and_b32 s2, s2, 0xf00
	s_or_b32 s2, s2, s3
	v_mov_b32_e32 v210, v167
	s_bfe_u32 s29, s2, 0x10008
	v_readfirstlane_b32 s4, v210
	s_ashr_i32 s2, s2, 9
	s_ashr_i32 s30, s4, 4
	s_lshl_b32 s4, s2, 1
	s_lshl_b32 s3, s3, 4
	s_or_b32 s4, s4, s29
	s_and_b32 s7, s3, 0xff0
	s_and_b32 s6, s30, -4
	s_ashr_i32 s5, s4, 31
	v_readlane_b32 s12, v230, 51
	s_add_i32 s28, s6, s7
	s_ashr_i32 s3, s2, 31
	s_lshl_b64 s[8:9], s[4:5], 15
	v_readlane_b32 s22, v230, 61
	v_readlane_b32 s23, v230, 62
	s_add_u32 s8, s22, s8
	s_addc_u32 s9, s23, s9
	s_lshl_b32 s7, s7, 3
	v_mov_b32_e32 v0, s7
	s_barrier
	v_cmp_eq_u32_e64 s[100:101], 0, v167
	s_and_saveexec_b64 s[100:101], s[100:101]
	s_cbranch_execz .Ltk_skip1
	global_atomic_add v250, v[252:253], v254, off sc0
; template <int MODE>
; DI void flash_loop(char* smem, const bf16_t* Kbase, size_t ldk, const bf16_t* Vtbase, size_t ldv, ull tiles, ull wtiles,
;                    const bf16x8 (&qf)[4], f32x16 (&o)[2], float& m, float& l, int tq, int tqmin, int tqmax, int maxdist, const float* cn_lds, ull lmask) {
;     ...
;   auto issue = [&](int kt, u32x4 (&rk)[2], u32x4 (&rv)[2]) {
; #pragma unroll
;     for (int q = 0; q < 2; ++q) { rk[q] = *(const u32x4*)(Kbase + (size_t)(64 * kt + lr + 32 * q) * ldk + c8); rv[q] = *(const u32x4*)(Vtbase + (size_t)(lr + 32 * q) * ldv + 64 * kt + c8); }
;   };
;   auto stash = [&](int stage, const u32x4 (&rk)[2], const u32x4 (&rv)[2]) {
;     bf16_t* Ks = (bf16_t*)(smem + stage * (2 * 64 * LSTR * 2)); bf16_t* Vs = Ks + 64 * LSTR;
; #pragma unroll
;     for (int q = 0; q < 2; ++q) { *(u32x4*)(Ks + (lr + 32 * q) * LSTR + c8) = rk[q]; *(u32x4*)(Vs + (lr + 32 * q) * LSTR + c8) = rv[q]; }
;   };
;   auto next_tile = [&]() -> int { if (!tiles) return -1; const int t = __builtin_ctzll(tiles); tiles &= tiles - 1; return t; };
;   auto compute = [&](int kt, int stage) {
;     if (!((wtiles >> kt) & 1ull)) return;
;     const bf16_t* Ks = (const bf16_t*)(smem + stage * (2 * 64 * LSTR * 2)); const bf16_t* Vs = Ks + 64 * LSTR;
;     const bool sel = ((lmask >> kt) & 1ull) != 0;
;     const bool interior = (64 * kt + 63 <= tqmin) && (MODE != 0 || (tqmax - 64 * kt <= maxdist));
;     int hm = 3;
;     if (MODE == 0) {
;       hm = 0;
;       if (64 * kt <= tqmax && 64 * kt + 31 >= tqmin - maxdist) hm |= 1;
;       if (64 * kt + 32 <= tqmax && 64 * kt + 63 >= tqmin - maxdist) hm |= 2;
;     }
;     if (MODE == 0 && hm == 1) attn_tile<MODE, true, 1>(Ks, Vs, qf, o, m, l, 64 * kt, tq, maxdist, cn_lds, sel);
;     else if (MODE == 0 && hm == 2) attn_tile<MODE, true, 2>(Ks, Vs, qf, o, m, l, 64 * kt, tq, maxdist, cn_lds, sel);
;     else if (interior) attn_tile<MODE, false>(Ks, Vs, qf, o, m, l, 64 * kt, tq, maxdist, cn_lds, sel);
; DI void nsa_slc_unit(const Params& p, int u, char* smem, bool probe = false) {
;     ...
;   const ull* sm = p.selmask + (size_t)(b * 2 + g) * SEQ + q0;
;   ull U = 0ull, Wm = 0ull;
; #pragma unroll
;   for (int i = 0; i < 16; ++i) U |= sm[i];
; #pragma unroll
;   for (int i = 0; i < 4; ++i) Wm |= sm[4 * w + i];
;   const ull lm = sm[4 * w + qi];
;   bf16x8 qf[4]; load_q(p.Q + tok * 1024 + head * 64, qf);
.Ltk_skip1:
	s_mov_b64 exec, s[100:101]
	global_load_dwordx4 v[2:5], v0, s[8:9] offset:48
	global_load_dwordx4 v[6:9], v0, s[8:9] offset:32
	global_load_dwordx4 v[10:13], v0, s[8:9] offset:16
	global_load_dwordx4 v[14:17], v0, s[8:9]
	global_load_dwordx4 v[18:21], v0, s[8:9] offset:112
	global_load_dwordx4 v[22:25], v0, s[8:9] offset:96
	global_load_dwordx4 v[26:29], v0, s[8:9] offset:80
	global_load_dwordx4 v[30:33], v0, s[8:9] offset:64
	s_add_u32 s10, s8, s7
	s_addc_u32 s11, s9, 0
	v_bfe_u32 v0, v210, 3, 2
	v_or_b32_e32 v186, s28, v0
	v_ashrrev_i32_e32 v187, 31, v186
	s_lshl_b64 s[8:9], s[2:3], 12
	v_lshl_add_u64 v[180:181], s[8:9], 0, v[186:187]
	v_and_b32_e32 v34, 7, v210
	v_lshl_or_b32 v209, s29, 3, v34
	v_lshlrev_b64 v[182:183], 10, v[180:181]
	v_readlane_b32 s13, v230, 52
	v_readlane_b32 s14, v230, 53
	v_readlane_b32 s15, v230, 54
	v_readlane_b32 s16, v230, 55
	v_readlane_b32 s17, v230, 56
	v_readlane_b32 s18, v230, 57
	v_readlane_b32 s19, v230, 58
	v_readlane_b32 s20, v230, 59
	v_readlane_b32 s21, v230, 60
	v_readlane_b32 s24, v230, 63
	v_readlane_b32 s25, v229, 0
	v_readlane_b32 s26, v229, 1
	v_readlane_b32 s27, v229, 2
	s_waitcnt vmcnt(7)
	v_readfirstlane_b32 s37, v3
	s_waitcnt vmcnt(6)
	v_readfirstlane_b32 s41, v7
	s_waitcnt vmcnt(5)
	v_readfirstlane_b32 s45, v11
	s_waitcnt vmcnt(4)
	v_readfirstlane_b32 s47, v17
	v_readfirstlane_b32 s46, v16
	v_readfirstlane_b32 s49, v15
	v_readfirstlane_b32 s48, v14
	v_readfirstlane_b32 s44, v10
	s_or_b64 s[46:47], s[46:47], s[48:49]
	v_readfirstlane_b32 s43, v13
	v_readfirstlane_b32 s42, v12
	s_or_b64 s[44:45], s[46:47], s[44:45]
	v_readfirstlane_b32 s40, v6
	s_or_b64 s[42:43], s[44:45], s[42:43]
	v_readfirstlane_b32 s39, v9
	v_readfirstlane_b32 s38, v8
	s_or_b64 s[40:41], s[42:43], s[40:41]
	v_readfirstlane_b32 s36, v2
	s_or_b64 s[38:39], s[40:41], s[38:39]
	v_readfirstlane_b32 s9, v5
	v_readfirstlane_b32 s8, v4
	s_or_b64 s[36:37], s[38:39], s[36:37]
	s_waitcnt vmcnt(0)
	v_readfirstlane_b32 s79, v31
	v_readfirstlane_b32 s78, v30
	s_or_b64 s[8:9], s[36:37], s[8:9]
	v_readfirstlane_b32 s75, v33
	v_readfirstlane_b32 s74, v32
	s_or_b64 s[8:9], s[8:9], s[78:79]
	v_readfirstlane_b32 s73, v27
	v_readfirstlane_b32 s72, v26
	s_or_b64 s[8:9], s[8:9], s[74:75]
	v_readfirstlane_b32 s71, v29
	v_readfirstlane_b32 s70, v28
	s_or_b64 s[8:9], s[8:9], s[72:73]
	v_readfirstlane_b32 s69, v23
	v_readfirstlane_b32 s68, v22
	s_or_b64 s[8:9], s[8:9], s[70:71]
	v_readfirstlane_b32 s63, v25
	v_readfirstlane_b32 s62, v24
	s_or_b64 s[8:9], s[8:9], s[68:69]
	v_readfirstlane_b32 s55, v19
	v_readfirstlane_b32 s54, v18
	s_or_b64 s[8:9], s[8:9], s[62:63]
	v_readfirstlane_b32 s51, v21
	v_readfirstlane_b32 s50, v20
	s_or_b64 s[8:9], s[8:9], s[54:55]
	s_or_b64 s[8:9], s[8:9], s[50:51]
	v_lshlrev_b32_e32 v2, 6, v209
	s_cmp_eq_u64 s[8:9], 0
	v_lshlrev_b32_e32 v184, 1, v2
	s_cbranch_scc1 .LBB0_811
	s_ashr_i32 s7, s6, 31
	s_lshl_b64 s[36:37], s[6:7], 3
	s_add_u32 s36, s10, s36
	s_addc_u32 s37, s11, s37
	s_or_b32 s30, s30, 3
	s_ashr_i32 s31, s30, 31
	s_lshl_b64 s[30:31], s[30:31], 3
	s_add_u32 s30, s10, s30
	s_addc_u32 s31, s11, s31
	v_or_b32_e32 v10, s6, v0
	s_lshl_b64 s[2:3], s[2:3], 20
	v_readlane_b32 s6, v230, 36
	s_add_u32 s2, s6, s2
	v_readlane_b32 s6, v230, 37
	s_addc_u32 s3, s6, s3
	s_lshl_b32 s6, s29, 7
	v_ashrrev_i32_e32 v11, 31, v10
	v_readlane_b32 s12, v229, 29
	s_add_u32 s2, s2, s6
	v_lshl_add_u64 v[10:11], v[10:11], 3, s[10:11]
	v_readlane_b32 s24, v229, 41
	v_readlane_b32 s25, v229, 42
	s_addc_u32 s3, s3, 0
	s_lshl_b64 s[4:5], s[4:5], 19
	global_load_dwordx2 v[6:7], v1, s[36:37] offset:16
	global_load_dwordx4 v[2:5], v1, s[36:37]
	global_load_dwordx2 v[8:9], v1, s[30:31]
	global_load_dwordx2 v[188:189], v[10:11], off
	v_lshl_add_u64 v[10:11], v[182:183], 1, s[24:25]
	v_mov_b32_e32 v185, v1
	s_add_u32 s6, s8, -1
	s_ff1_i32_b64 s11, s[8:9]
	v_lshl_add_u64 v[10:11], v[10:11], 0, v[184:185]
	v_lshlrev_b32_e32 v0, 1, v166
	s_addc_u32 s7, s9, -1
	s_lshl_b32 s10, s11, 6
	v_lshl_add_u64 v[10:11], v[10:11], 0, v[0:1]
	v_add_lshl_u32 v0, s10, v169, 8
	global_load_dwordx4 v[98:101], v[10:11], off
	global_load_dwordx4 v[102:105], v[10:11], off offset:32
	global_load_dwordx4 v[106:109], v[10:11], off offset:64
	global_load_dwordx4 v[110:113], v[10:11], off offset:96
	v_lshl_add_u64 v[10:11], s[2:3], 0, v[0:1]
	v_lshlrev_b32_e32 v0, 1, v168
	v_lshl_add_u64 v[10:11], v[10:11], 0, v[0:1]
	global_load_dwordx4 v[114:117], v[10:11], off
	v_lshl_add_u64 v[10:11], v[172:173], 0, s[4:5]
	s_lshl_b32 s58, s11, 7
	v_lshl_add_u64 v[12:13], v[10:11], 0, s[58:59]
	v_lshl_add_u64 v[12:13], v[12:13], 0, v[0:1]
	global_load_dwordx4 v[118:121], v[12:13], off
	v_add_lshl_u32 v12, s10, v171, 8
	v_mov_b32_e32 v13, v1
	v_lshl_add_u64 v[12:13], s[2:3], 0, v[12:13]
	v_lshl_add_u64 v[12:13], v[12:13], 0, v[0:1]
	s_mov_b64 s[4:5], 0x40000
	global_load_dwordx4 v[122:125], v[12:13], off
	v_lshl_add_u64 v[12:13], v[10:11], 0, s[4:5]
	v_lshl_add_u64 v[14:15], v[12:13], 0, s[58:59]
	v_lshl_add_u64 v[14:15], v[14:15], 0, v[0:1]
	global_load_dwordx4 v[126:129], v[14:15], off
	s_and_b64 s[4:5], s[6:7], s[8:9]
	s_ff1_i32_b64 s6, s[4:5]
	s_cmp_lg_u64 s[4:5], 0
	s_cselect_b32 s6, s6, -1
	s_cmp_lt_i32 s6, 0
	v_readlane_b32 s13, v229, 30
	v_readlane_b32 s14, v229, 31
	v_readlane_b32 s15, v229, 32
	v_readlane_b32 s16, v229, 33
	v_readlane_b32 s17, v229, 34
	v_readlane_b32 s18, v229, 35
	v_readlane_b32 s19, v229, 36
	v_readlane_b32 s20, v229, 37
	v_readlane_b32 s21, v229, 38
	v_readlane_b32 s22, v229, 39
	v_readlane_b32 s23, v229, 40
	v_readlane_b32 s26, v229, 43
	v_readlane_b32 s27, v229, 44
	s_cbranch_scc1 .LBB0_818
	s_lshl_b32 s7, s6, 6
	v_add_u32_e32 v14, s7, v169
	v_mov_b32_e32 v15, v1
	v_lshlrev_b64 v[14:15], 8, v[14:15]
	v_lshl_add_u64 v[14:15], s[2:3], 0, v[14:15]
	v_lshl_add_u64 v[14:15], v[14:15], 0, v[0:1]
	s_lshl_b32 s58, s6, 7
	global_load_dwordx4 v[130:133], v[14:15], off
	v_lshl_add_u64 v[14:15], v[10:11], 0, s[58:59]
	v_lshl_add_u64 v[14:15], v[14:15], 0, v[0:1]
	global_load_dwordx4 v[134:137], v[14:15], off
	v_add_u32_e32 v14, s7, v171
	v_mov_b32_e32 v15, v1
	v_lshlrev_b64 v[14:15], 8, v[14:15]
	v_lshl_add_u64 v[14:15], s[2:3], 0, v[14:15]
	v_lshl_add_u64 v[14:15], v[14:15], 0, v[0:1]
	global_load_dwordx4 v[138:141], v[14:15], off
	v_lshl_add_u64 v[14:15], v[12:13], 0, s[58:59]
	v_lshl_add_u64 v[14:15], v[14:15], 0, v[0:1]
	global_load_dwordx4 v[142:145], v[14:15], off
	s_branch .LBB0_819
